# v29 + hgC items: the ten global loads (state fragments, q/e/i rows) issued one item ahead into spare registers and copied at the item top, as the other item loops already do
# baseline (speedup 1.0000x reference)
; __device__ __forceinline__ int bid_s() { int b = blockIdx.x; asm volatile("" : "+s"(b)); return b; }
; __device__ __forceinline__ void hgC_item(const Bufs& B, int l, int it, unsigned char* shm, const float* hlb, const float* hn) {
;     ...
;     bf16x8 sf[4]; load_bfrag<4>(sf, B.St + (size_t)it * 16384 + wid * 16 * 128, 128, lane);
;     u32x4 ev[2], iv[2], qv[2];
; #pragma unroll
;     for (int q = 0; q < 2; ++q) { const int idx = tid + 512 * q; const bf16_t* rowp = B.bufD + (size_t)(m0 + (idx >> 4)) * 1536 + h * 128 + (idx & 15) * 8; qv[q] = *(const u32x4*)rowp; ev[q] = *(const u32x4*)(rowp + 512); iv[q] = *(const u32x4*)(rowp + 1024); }
; __device__ __forceinline__ void phase4(int l, unsigned char* shm) {
;     ...
;     const float* hlb = IN(21);
;     for (int it = bid_s(); it < 1024; it += gridDim.x) hgC_item(B, l, it, shm, hlb, hn);
.LBB0_817:
	s_or_b64 exec, exec, s[16:17]
	s_load_dwordx2 s[16:17], s[0:1], 0xa8
	s_waitcnt lgkmcnt(0)
	s_mov_b32 s18, s87
	s_cmpk_gt_i32 s18, 0x3ff
	v_readlane_b32 s46, v255, 25
	v_readlane_b32 s47, v255, 26
	s_cbranch_scc1 .LBB0_836
	s_add_u32 s27, s22, 0xec00000
	s_addc_u32 s29, s23, 0
	s_add_u32 s42, s22, 0x1dc00000
	s_addc_u32 s43, s23, 0
	s_lshl_b64 s[2:3], s[30:31], 2
	s_add_u32 s44, s20, s2
	s_addc_u32 s45, s21, s3
	v_readlane_b32 s2, v255, 37
	s_cmp_gt_u32 s2, 1
	s_cselect_b64 s[20:21], -1, 0
	s_add_u32 s22, s22, 0x1cc00000
	s_addc_u32 s23, s23, 0
	s_mov_b32 s36, s18
	s_lshl_b32 s34, s36, 15
	s_add_u32 s38, s42, s34
	s_addc_u32 s39, s43, 0
	v_lshrrev_b32_e32 v168, 6, v179
	v_and_b32_e32 v169, 15, v179
	v_bfe_u32 v170, v179, 4, 2
	v_lshlrev_b32_e32 v168, 12, v168
	v_lshl_add_u32 v168, v169, 8, v168
	v_lshl_add_u32 v168, v170, 4, v168
	global_load_dwordx4 v[128:131], v168, s[38:39]
	global_load_dwordx4 v[132:135], v168, s[38:39] offset:64
	global_load_dwordx4 v[136:139], v168, s[38:39] offset:128
	global_load_dwordx4 v[140:143], v168, s[38:39] offset:192
	s_lshl_b32 s34, s36, 4
	s_and_b32 s34, s34, 0xfffff800
	s_lshl_b32 s35, s36, 6
	s_and_b32 s35, s35, 0x7c0
	s_or_b32 s34, s34, s35
	s_mul_i32 s34, s34, 0xc00
	s_lshl_b32 s35, s36, 3
	s_and_b32 s35, s35, 0x300
	s_add_u32 s34, s34, s35
	s_add_u32 s38, s27, s34
	s_addc_u32 s39, s29, 0
	v_lshrrev_b32_e32 v170, 4, v179
	v_mul_u32_u24_e32 v170, 0xc00, v170
	v_lshl_add_u32 v169, v169, 4, v170
	v_add_u32_e32 v170, 0x18000, v169
	global_load_dwordx4 v[144:147], v169, s[38:39]
	global_load_dwordx4 v[148:151], v169, s[38:39] offset:1024
	global_load_dwordx4 v[152:155], v169, s[38:39] offset:2048
	global_load_dwordx4 v[156:159], v170, s[38:39]
	global_load_dwordx4 v[160:163], v170, s[38:39] offset:1024
	global_load_dwordx4 v[164:167], v170, s[38:39] offset:2048
	s_waitcnt vmcnt(0)
	s_branch .LBB0_820

; __device__ __forceinline__ float sigm(float x) { return __builtin_amdgcn_rcpf(1.0f + __expf(-x)); }
; __device__ __forceinline__ void hg_cum(const u32x4 (&ev)[2], int l, int h, const float* hlb, float* cumS, float* lbS, int tid) {
;     __syncthreads();
;     if (tid < 128) lbS[tid] = l == 0 ? 1.0f : 1.0f - sigm(hlb[512 + h * 128 + tid] - hlb[h * 128 + tid]);
; __device__ __forceinline__ void hgC_item(const Bufs& B, int l, int it, unsigned char* shm, const float* hlb, const float* hn) {
;     ...
;     bf16x8 sf[4]; load_bfrag<4>(sf, B.St + (size_t)it * 16384 + wid * 16 * 128, 128, lane);
;     u32x4 ev[2], iv[2], qv[2];
; #pragma unroll
;     for (int q = 0; q < 2; ++q) { const int idx = tid + 512 * q; const bf16_t* rowp = B.bufD + (size_t)(m0 + (idx >> 4)) * 1536 + h * 128 + (idx & 15) * 8; qv[q] = *(const u32x4*)rowp; ev[q] = *(const u32x4*)(rowp + 512); iv[q] = *(const u32x4*)(rowp + 1024); }
.LBB0_820:
	s_lshl_b32 s2, s18, 4
	s_lshl_b32 s3, s18, 6
	v_mov_b32_e32 v67, v179
	s_and_b32 s2, s2, 0xfffff800
	s_and_b32 s3, s3, 0x7c0
	s_ashr_i32 s19, s18, 31
	s_or_b32 s34, s2, s3
	v_ashrrev_i32_e32 v66, 6, v67
	s_lshl_b64 s[2:3], s[18:19], 15
	s_add_u32 s2, s42, s2
	v_lshlrev_b32_e32 v0, 11, v66
	s_addc_u32 s3, s43, s3
	v_ashrrev_i32_e32 v1, 31, v0
	v_lshl_add_u64 v[0:1], v[0:1], 1, s[2:3]
	s_lshl_b32 s2, s18, 2
	s_and_b32 s19, s2, 0x180
	s_lshl_b32 s30, s19, 1
	v_lshlrev_b32_e32 v68, 3, v67
	v_lshlrev_b32_e32 v2, 8, v67
	s_add_u32 s2, s27, s30
	v_and_b32_e32 v65, 0x78, v68
	v_and_b32_e32 v176, 0xf00, v2
	v_lshrrev_b32_e32 v2, 1, v67
	s_addc_u32 s3, s29, 0
	v_lshlrev_b32_e32 v42, 1, v65
	v_mov_b32_e32 v43, v177
	v_add_u32_e32 v40, 0x200, v67
	v_and_b32_e32 v64, 24, v2
	s_waitcnt vmcnt(2)
	v_lshl_add_u64 v[16:17], s[2:3], 0, v[42:43]
	v_ashrrev_i32_e32 v43, 4, v67
	v_ashrrev_i32_e32 v49, 4, v40
	v_lshl_add_u64 v[0:1], v[0:1], 0, v[176:177]
	v_lshlrev_b32_e32 v176, 1, v64
	v_add_u32_e32 v46, s34, v43
	v_add_u32_e32 v44, s34, v49
	v_lshl_add_u64 v[12:13], v[0:1], 0, v[176:177]
	v_mad_i64_i32 v[18:19], s[2:3], v46, s59, v[16:17]
	v_mad_i64_i32 v[16:17], s[2:3], v44, s59, v[16:17]
	s_waitcnt vmcnt(2)
	v_mov_b64_e32 v[0:1], v[128:129]
	v_mov_b64_e32 v[2:3], v[130:131]
	v_mov_b64_e32 v[4:5], v[132:133]
	v_mov_b64_e32 v[6:7], v[134:135]
	v_mov_b64_e32 v[8:9], v[136:137]
	v_mov_b64_e32 v[10:11], v[138:139]
	s_nop 0
	v_mov_b64_e32 v[12:13], v[140:141]
	v_mov_b64_e32 v[14:15], v[142:143]
	s_nop 0
	v_mov_b64_e32 v[28:29], v[144:145]
	v_mov_b64_e32 v[30:31], v[146:147]
	v_mov_b64_e32 v[36:37], v[148:149]
	v_mov_b64_e32 v[38:39], v[150:151]
	v_mov_b64_e32 v[24:25], v[152:153]
	v_mov_b64_e32 v[26:27], v[154:155]
	v_mov_b64_e32 v[20:21], v[156:157]
	v_mov_b64_e32 v[22:23], v[158:159]
	v_mov_b64_e32 v[32:33], v[160:161]
	v_mov_b64_e32 v[34:35], v[162:163]
	s_nop 0
	v_mov_b64_e32 v[16:17], v[164:165]
	v_mov_b64_e32 v[18:19], v[166:167]
	v_cmp_gt_i32_e32 vcc, s88, v67
	s_barrier
	s_and_saveexec_b64 s[2:3], vcc
	s_cbranch_execz .LBB0_824
	s_andn2_b64 vcc, exec, s[20:21]
	v_mov_b32_e32 v41, 1.0
	s_cbranch_vccnz .LBB0_823
	v_add_u32_e32 v40, s19, v40
	v_ashrrev_i32_e32 v41, 31, v40
	v_lshl_add_u64 v[40:41], v[40:41], 2, s[16:17]
	global_load_dword v45, v[40:41], off
	v_add_u32_e32 v40, s19, v67
	v_ashrrev_i32_e32 v41, 31, v40
	v_lshl_add_u64 v[40:41], v[40:41], 2, s[16:17]
	global_load_dword v40, v[40:41], off
	s_waitcnt vmcnt(0)
	v_sub_f32_e32 v40, v45, v40
	v_mul_f32_e32 v40, 0xbfb8aa3b, v40
	v_exp_f32_e32 v40, v40
	s_nop 0
	v_add_f32_e32 v40, 1.0, v40
	v_rcp_f32_e32 v40, v40
	s_nop 0
	v_sub_f32_e32 v41, 1.0, v40

; __device__ __forceinline__ void unpack8(const u32x4& w, f32x4& v0, f32x4& v1) { v0[0] = bflo(w.x); v0[1] = bfhi(w.x); v0[2] = bflo(w.y); v0[3] = bfhi(w.y); v1[0] = bflo(w.z); v1[1] = bfhi(w.z); v1[2] = bflo(w.w); v1[3] = bfhi(w.w); }
; __device__ __forceinline__ void hg_cum(const u32x4 (&ev)[2], int l, int h, const float* hlb, float* cumS, float* lbS, int tid) {
;     ...
; #pragma unroll
;     for (int q = 0; q < 2; ++q) {
;         const int idx = tid + 512 * q, t = idx >> 4, k8 = (idx & 15) * 8;
;         f32x4 a, bb; unpack8(ev[q], a, bb);
;         const f32x4 l0 = *(const f32x4*)(lbS + k8), l1 = *(const f32x4*)(lbS + k8 + 4);
; #pragma unroll
;         for (int j = 0; j < 4; ++j) { a[j] = __logf(fmaxf(1.0f - l0[j] * a[j], 1e-30f)); bb[j] = __logf(fmaxf(1.0f - l1[j] * bb[j], 1e-30f)); }
;         *(f32x4*)(cumS + t * 128 + k8) = a; *(f32x4*)(cumS + t * 128 + k8 + 4) = bb;
; __device__ __forceinline__ void hgC_item(const Bufs& B, int l, int it, unsigned char* shm, const float* hlb, const float* hn) {
;     ...
;     bf16x8 sf[4]; load_bfrag<4>(sf, B.St + (size_t)it * 16384 + wid * 16 * 128, 128, lane);
;     u32x4 ev[2], iv[2], qv[2];
; #pragma unroll
;     for (int q = 0; q < 2; ++q) { const int idx = tid + 512 * q; const bf16_t* rowp = B.bufD + (size_t)(m0 + (idx >> 4)) * 1536 + h * 128 + (idx & 15) * 8; qv[q] = *(const u32x4*)rowp; ev[q] = *(const u32x4*)(rowp + 512); iv[q] = *(const u32x4*)(rowp + 1024); }
.LBB0_824:
	s_or_b64 exec, exec, s[2:3]
	v_lshl_add_u32 v48, v65, 2, 0
	v_add_u32_e32 v69, 0x1bc00, v48
	s_waitcnt lgkmcnt(0)
	s_barrier
	v_lshlrev_b32_e32 v54, 16, v38
	v_and_b32_e32 v55, 0xffff0000, v38
	v_lshlrev_b32_e32 v50, 16, v39
	v_and_b32_e32 v51, 0xffff0000, v39
	ds_read_b128 v[58:61], v69
	ds_read_b128 v[38:41], v69 offset:16
	v_lshlrev_b32_e32 v56, 16, v36
	v_and_b32_e32 v57, 0xffff0000, v36
	v_lshlrev_b32_e32 v52, 16, v37
	s_waitcnt lgkmcnt(1)
	v_fma_f32 v36, -v58, v56, 1.0
	v_max_f32_e32 v36, 0xda24260, v36
	v_cmp_gt_f32_e32 vcc, s33, v36
	v_and_b32_e32 v53, 0xffff0000, v37
	s_waitcnt lgkmcnt(0)
	v_fma_f32 v38, -v38, v54, 1.0
	v_cndmask_b32_e64 v37, 0, 32, vcc
	v_ldexp_f32 v36, v36, v37
	v_log_f32_e32 v36, v36
	v_max_f32_e32 v38, 0xda24260, v38
	v_fma_f32 v40, -v40, v50, 1.0
	v_max_f32_e32 v40, 0xda24260, v40
	v_mul_f32_e32 v37, 0x3f317217, v36
	v_fma_f32 v37, v36, s79, -v37
	v_fmac_f32_e32 v37, 0x3377d1cf, v36
	v_fmac_f32_e32 v37, 0x3f317217, v36
	v_cmp_lt_f32_e64 s[40:41], |v36|, s80
	s_add_i32 s36, s18, s72
	s_cmpk_lt_i32 s36, 0x400
	s_cselect_b32 s36, s36, s18
	s_lshl_b32 s34, s36, 15
	s_add_u32 s38, s42, s34
	s_addc_u32 s39, s43, 0
	v_lshrrev_b32_e32 v168, 6, v179
	v_and_b32_e32 v169, 15, v179
	v_bfe_u32 v170, v179, 4, 2
	v_lshlrev_b32_e32 v168, 12, v168
	v_lshl_add_u32 v168, v169, 8, v168
	v_lshl_add_u32 v168, v170, 4, v168
	global_load_dwordx4 v[128:131], v168, s[38:39]
	global_load_dwordx4 v[132:135], v168, s[38:39] offset:64
	global_load_dwordx4 v[136:139], v168, s[38:39] offset:128
	global_load_dwordx4 v[140:143], v168, s[38:39] offset:192
	s_lshl_b32 s34, s36, 4
	s_and_b32 s34, s34, 0xfffff800
	s_lshl_b32 s35, s36, 6
	s_and_b32 s35, s35, 0x7c0
	s_or_b32 s34, s34, s35
	s_mul_i32 s34, s34, 0xc00
	s_lshl_b32 s35, s36, 3
	s_and_b32 s35, s35, 0x300
	s_add_u32 s34, s34, s35
	s_add_u32 s38, s27, s34
	s_addc_u32 s39, s29, 0
	v_lshrrev_b32_e32 v170, 4, v179
	v_mul_u32_u24_e32 v170, 0xc00, v170
	v_lshl_add_u32 v169, v169, 4, v170
	v_add_u32_e32 v170, 0x18000, v169
	global_load_dwordx4 v[144:147], v169, s[38:39]
	global_load_dwordx4 v[148:151], v169, s[38:39] offset:1024
	global_load_dwordx4 v[152:155], v169, s[38:39] offset:2048
	global_load_dwordx4 v[156:159], v170, s[38:39]
	global_load_dwordx4 v[160:163], v170, s[38:39] offset:1024
	global_load_dwordx4 v[164:167], v170, s[38:39] offset:2048
	v_lshlrev_b32_e32 v62, 16, v32
	v_and_b32_e32 v63, 0xffff0000, v32
	v_cndmask_b32_e64 v36, v36, v37, s[40:41]
	v_cndmask_b32_e32 v37, 0, v212, vcc
	v_sub_f32_e32 v36, v36, v37
	v_fma_f32 v37, -v59, v57, 1.0
	v_max_f32_e32 v37, 0xda24260, v37
	v_cmp_gt_f32_e32 vcc, s33, v37
	v_ashrrev_i32_e32 v47, 31, v46
	v_ashrrev_i32_e32 v45, 31, v44
	v_cndmask_b32_e64 v58, 0, 32, vcc
	v_ldexp_f32 v37, v37, v58
	v_log_f32_e32 v37, v37
	s_nop 0
	v_mul_f32_e32 v58, 0x3f317217, v37
	v_fma_f32 v58, v37, s79, -v58
	v_fmac_f32_e32 v58, 0x3377d1cf, v37
	v_fmac_f32_e32 v58, 0x3f317217, v37
	v_cmp_lt_f32_e64 s[40:41], |v37|, s80
	s_nop 1
	v_cndmask_b32_e64 v37, v37, v58, s[40:41]
	v_cndmask_b32_e32 v58, 0, v212, vcc
	v_cmp_gt_f32_e32 vcc, s33, v38
	v_sub_f32_e32 v37, v37, v58
	s_nop 0
	v_cndmask_b32_e64 v58, 0, 32, vcc
	v_ldexp_f32 v38, v38, v58
	v_log_f32_e32 v38, v38
	s_nop 0
	v_mul_f32_e32 v58, 0x3f317217, v38
	v_fma_f32 v58, v38, s79, -v58
	v_fmac_f32_e32 v58, 0x3377d1cf, v38
	v_fmac_f32_e32 v58, 0x3f317217, v38
	v_cmp_lt_f32_e64 s[40:41], |v38|, s80
	s_nop 1
	v_cndmask_b32_e64 v38, v38, v58, s[40:41]
	v_cndmask_b32_e32 v58, 0, v212, vcc
	v_sub_f32_e32 v58, v38, v58
	v_fma_f32 v38, -v39, v55, 1.0
	v_max_f32_e32 v38, 0xda24260, v38
	v_cmp_gt_f32_e32 vcc, s33, v38
	s_nop 1
	v_cndmask_b32_e64 v39, 0, 32, vcc
	v_ldexp_f32 v38, v38, v39
	v_log_f32_e32 v38, v38
	s_nop 0
	v_mul_f32_e32 v39, 0x3f317217, v38
	v_fma_f32 v39, v38, s79, -v39
	v_fmac_f32_e32 v39, 0x3377d1cf, v38
	v_fmac_f32_e32 v39, 0x3f317217, v38
	v_cmp_lt_f32_e64 s[40:41], |v38|, s80
	s_nop 1
	v_cndmask_b32_e64 v38, v38, v39, s[40:41]
	v_cndmask_b32_e32 v39, 0, v212, vcc
	v_sub_f32_e32 v59, v38, v39
	v_fma_f32 v38, -v60, v52, 1.0
	v_max_f32_e32 v38, 0xda24260, v38
	v_cmp_gt_f32_e32 vcc, s33, v38
	s_nop 1
	v_cndmask_b32_e64 v39, 0, 32, vcc
	v_ldexp_f32 v38, v38, v39
	v_log_f32_e32 v38, v38
	s_nop 0
	v_mul_f32_e32 v39, 0x3f317217, v38
	v_fma_f32 v39, v38, s79, -v39
	v_fmac_f32_e32 v39, 0x3377d1cf, v38
	v_fmac_f32_e32 v39, 0x3f317217, v38
	v_cmp_lt_f32_e64 s[40:41], |v38|, s80
	s_nop 1
	v_cndmask_b32_e64 v38, v38, v39, s[40:41]
	v_cndmask_b32_e32 v39, 0, v212, vcc
	v_sub_f32_e32 v38, v38, v39
	v_fma_f32 v39, -v61, v53, 1.0
	v_max_f32_e32 v39, 0xda24260, v39
	v_cmp_gt_f32_e32 vcc, s33, v39
	s_nop 1
	v_cndmask_b32_e64 v60, 0, 32, vcc
	v_ldexp_f32 v39, v39, v60
	v_log_f32_e32 v39, v39
	s_nop 0
	v_mul_f32_e32 v60, 0x3f317217, v39
	v_fma_f32 v60, v39, s79, -v60
	v_fmac_f32_e32 v60, 0x3377d1cf, v39
	v_fmac_f32_e32 v60, 0x3f317217, v39
	v_cmp_lt_f32_e64 s[40:41], |v39|, s80
	s_nop 1
	v_cndmask_b32_e64 v39, v39, v60, s[40:41]
	v_cndmask_b32_e32 v60, 0, v212, vcc
	v_cmp_gt_f32_e32 vcc, s33, v40
	v_sub_f32_e32 v39, v39, v60
	s_nop 0
	v_cndmask_b32_e64 v60, 0, 32, vcc
	v_ldexp_f32 v40, v40, v60
	v_log_f32_e32 v40, v40
	s_nop 0
	v_mul_f32_e32 v60, 0x3f317217, v40
	v_fma_f32 v60, v40, s79, -v60
	v_fmac_f32_e32 v60, 0x3377d1cf, v40
	v_fmac_f32_e32 v60, 0x3f317217, v40
	v_cmp_lt_f32_e64 s[40:41], |v40|, s80
	s_nop 1
	v_cndmask_b32_e64 v40, v40, v60, s[40:41]
	v_cndmask_b32_e32 v60, 0, v212, vcc
	v_sub_f32_e32 v60, v40, v60
	v_fma_f32 v40, -v41, v51, 1.0
	v_max_f32_e32 v40, 0xda24260, v40
	v_cmp_gt_f32_e32 vcc, s33, v40
	s_nop 1
	v_cndmask_b32_e64 v41, 0, 32, vcc
	v_ldexp_f32 v40, v40, v41
	v_log_f32_e32 v40, v40
	s_nop 0
	v_mul_f32_e32 v41, 0x3f317217, v40
	v_fma_f32 v41, v40, s79, -v41
	v_fmac_f32_e32 v41, 0x3377d1cf, v40
	v_fmac_f32_e32 v41, 0x3f317217, v40
	v_cmp_lt_f32_e64 s[40:41], |v40|, s80
	s_nop 1
	v_cndmask_b32_e64 v40, v40, v41, s[40:41]
	v_cndmask_b32_e32 v41, 0, v212, vcc
	v_sub_f32_e32 v61, v40, v41
	v_and_b32_e32 v40, 0x3fffff80, v68
	v_lshl_add_u32 v70, v40, 2, v48
	ds_write_b128 v70, v[36:39]
	ds_write_b128 v70, v[58:61] offset:16
	v_lshlrev_b32_e32 v58, 16, v33
	v_and_b32_e32 v59, 0xffff0000, v33
	v_lshlrev_b32_e32 v60, 16, v34
	v_and_b32_e32 v61, 0xffff0000, v34
	v_lshlrev_b32_e32 v40, 16, v35
	v_and_b32_e32 v41, 0xffff0000, v35
	ds_read_b128 v[36:39], v69
	ds_read_b128 v[32:35], v69 offset:16
	s_waitcnt lgkmcnt(1)
; __device__ __forceinline__ void unpack8(const u32x4& w, f32x4& v0, f32x4& v1) { v0[0] = bflo(w.x); v0[1] = bfhi(w.x); v0[2] = bflo(w.y); v0[3] = bfhi(w.y); v1[0] = bflo(w.z); v1[1] = bfhi(w.z); v1[2] = bflo(w.w); v1[3] = bfhi(w.w); }
; __device__ __forceinline__ void hg_cum(const u32x4 (&ev)[2], int l, int h, const float* hlb, float* cumS, float* lbS, int tid) {
;     ...
;         const int idx = tid + 512 * q, t = idx >> 4, k8 = (idx & 15) * 8;
;         f32x4 a, bb; unpack8(ev[q], a, bb);
;         const f32x4 l0 = *(const f32x4*)(lbS + k8), l1 = *(const f32x4*)(lbS + k8 + 4);
; #pragma unroll
;         for (int j = 0; j < 4; ++j) { a[j] = __logf(fmaxf(1.0f - l0[j] * a[j], 1e-30f)); bb[j] = __logf(fmaxf(1.0f - l1[j] * bb[j], 1e-30f)); }
;         *(f32x4*)(cumS + t * 128 + k8) = a; *(f32x4*)(cumS + t * 128 + k8 + 4) = bb;
;     }
;     __syncthreads();
;     const int k = tid & 127, seg = tid >> 7;
;     { float run = 0.f;
; #pragma unroll
;       for (int tt = 0; tt < 16; ++tt) { const int t = seg * 16 + tt; run += cumS[t * 128 + k]; cumS[t * 128 + k] = run; } }
;     __syncthreads();
;     float off = 0.f;
;     for (int sp = 0; sp < seg; ++sp) off += cumS[(16 * sp + 15) * 128 + k];
	v_fma_f32 v36, -v36, v62, 1.0
	v_max_f32_e32 v36, 0xda24260, v36
	v_cmp_gt_f32_e32 vcc, s33, v36
	v_fma_f32 v37, -v37, v63, 1.0
	v_max_f32_e32 v37, 0xda24260, v37
	v_cndmask_b32_e64 v71, 0, 32, vcc
	v_ldexp_f32 v36, v36, v71
	v_log_f32_e32 v36, v36
	s_waitcnt lgkmcnt(0)
	v_fma_f32 v32, -v32, v60, 1.0
	v_max_f32_e32 v32, 0xda24260, v32
	v_fma_f32 v33, -v33, v61, 1.0
	v_mul_f32_e32 v71, 0x3f317217, v36
	v_fma_f32 v71, v36, s79, -v71
	v_fmac_f32_e32 v71, 0x3377d1cf, v36
	v_fmac_f32_e32 v71, 0x3f317217, v36
	v_cmp_lt_f32_e64 s[40:41], |v36|, s80
	v_max_f32_e32 v33, 0xda24260, v33
	v_fma_f32 v38, -v38, v58, 1.0
	v_cndmask_b32_e64 v36, v36, v71, s[40:41]
	v_cndmask_b32_e32 v71, 0, v212, vcc
	v_cmp_gt_f32_e32 vcc, s33, v37
	v_sub_f32_e32 v36, v36, v71
	v_max_f32_e32 v38, 0xda24260, v38
	v_cndmask_b32_e64 v71, 0, 32, vcc
	v_ldexp_f32 v37, v37, v71
	v_log_f32_e32 v37, v37
	v_fma_f32 v39, -v39, v59, 1.0
	v_max_f32_e32 v39, 0xda24260, v39
	v_fma_f32 v34, -v34, v40, 1.0
	v_mul_f32_e32 v71, 0x3f317217, v37
	v_fma_f32 v71, v37, s79, -v71
	v_fmac_f32_e32 v71, 0x3377d1cf, v37
	v_fmac_f32_e32 v71, 0x3f317217, v37
	v_cmp_lt_f32_e64 s[40:41], |v37|, s80
	v_max_f32_e32 v34, 0xda24260, v34
	v_fma_f32 v35, -v35, v41, 1.0
	v_cndmask_b32_e64 v37, v37, v71, s[40:41]
	v_cndmask_b32_e32 v71, 0, v212, vcc
	v_cmp_gt_f32_e32 vcc, s33, v32
	v_sub_f32_e32 v37, v37, v71
	v_max_f32_e32 v35, 0xda24260, v35
	v_cndmask_b32_e64 v71, 0, 32, vcc
	v_ldexp_f32 v32, v32, v71
	v_log_f32_e32 v32, v32
	s_nop 0
	v_mul_f32_e32 v71, 0x3f317217, v32
	v_fma_f32 v71, v32, s79, -v71
	v_fmac_f32_e32 v71, 0x3377d1cf, v32
	v_fmac_f32_e32 v71, 0x3f317217, v32
	v_cmp_lt_f32_e64 s[40:41], |v32|, s80
	s_nop 1
	v_cndmask_b32_e64 v32, v32, v71, s[40:41]
	v_cndmask_b32_e32 v71, 0, v212, vcc
	v_cmp_gt_f32_e32 vcc, s33, v33
	v_sub_f32_e32 v32, v32, v71
	s_nop 0
	v_cndmask_b32_e64 v71, 0, 32, vcc
	v_ldexp_f32 v33, v33, v71
	v_log_f32_e32 v33, v33
	s_nop 0
	v_mul_f32_e32 v71, 0x3f317217, v33
	v_fma_f32 v71, v33, s79, -v71
	v_fmac_f32_e32 v71, 0x3377d1cf, v33
	v_fmac_f32_e32 v71, 0x3f317217, v33
	v_cmp_lt_f32_e64 s[40:41], |v33|, s80
	s_nop 1
	v_cndmask_b32_e64 v33, v33, v71, s[40:41]
	v_cndmask_b32_e32 v71, 0, v212, vcc
	v_cmp_gt_f32_e32 vcc, s33, v38
	v_sub_f32_e32 v33, v33, v71
	s_nop 0
	v_cndmask_b32_e64 v71, 0, 32, vcc
	v_ldexp_f32 v38, v38, v71
	v_log_f32_e32 v38, v38
	s_nop 0
	v_mul_f32_e32 v71, 0x3f317217, v38
	v_fma_f32 v71, v38, s79, -v71
	v_fmac_f32_e32 v71, 0x3377d1cf, v38
	v_fmac_f32_e32 v71, 0x3f317217, v38
	v_cmp_lt_f32_e64 s[40:41], |v38|, s80
	s_nop 1
	v_cndmask_b32_e64 v38, v38, v71, s[40:41]
	v_cndmask_b32_e32 v71, 0, v212, vcc
	v_cmp_gt_f32_e32 vcc, s33, v39
	v_sub_f32_e32 v38, v38, v71
	s_nop 0
	v_cndmask_b32_e64 v71, 0, 32, vcc
	v_ldexp_f32 v39, v39, v71
	v_log_f32_e32 v39, v39
	s_nop 0
	v_mul_f32_e32 v71, 0x3f317217, v39
	v_fma_f32 v71, v39, s79, -v71
	v_fmac_f32_e32 v71, 0x3377d1cf, v39
	v_fmac_f32_e32 v71, 0x3f317217, v39
	v_cmp_lt_f32_e64 s[40:41], |v39|, s80
	s_nop 1
	v_cndmask_b32_e64 v39, v39, v71, s[40:41]
	v_cndmask_b32_e32 v71, 0, v212, vcc
	v_cmp_gt_f32_e32 vcc, s33, v34
	v_sub_f32_e32 v39, v39, v71
	s_nop 0
	v_cndmask_b32_e64 v71, 0, 32, vcc
	v_ldexp_f32 v34, v34, v71
	v_log_f32_e32 v34, v34
	s_nop 0
	v_mul_f32_e32 v71, 0x3f317217, v34
	v_fma_f32 v71, v34, s79, -v71
	v_fmac_f32_e32 v71, 0x3377d1cf, v34
	v_fmac_f32_e32 v71, 0x3f317217, v34
	v_cmp_lt_f32_e64 s[40:41], |v34|, s80
	s_nop 1
	v_cndmask_b32_e64 v34, v34, v71, s[40:41]
	v_cndmask_b32_e32 v71, 0, v212, vcc
	v_cmp_gt_f32_e32 vcc, s33, v35
	v_sub_f32_e32 v34, v34, v71
	s_nop 0
	v_cndmask_b32_e64 v71, 0, 32, vcc
	v_ldexp_f32 v35, v35, v71
	v_log_f32_e32 v35, v35
	s_nop 0
	v_mul_f32_e32 v71, 0x3f317217, v35
	v_fma_f32 v71, v35, s79, -v71
	v_fmac_f32_e32 v71, 0x3377d1cf, v35
	v_fmac_f32_e32 v71, 0x3f317217, v35
	v_cmp_lt_f32_e64 s[40:41], |v35|, s80
	s_nop 1
	v_cndmask_b32_e64 v35, v35, v71, s[40:41]
	v_cndmask_b32_e32 v71, 0, v212, vcc
	v_sub_f32_e32 v35, v35, v71
	ds_write_b128 v70, v[36:39] offset:16384
	ds_write_b128 v70, v[32:35] offset:16400
	v_and_b32_e32 v35, 0x7f, v67
	v_ashrrev_i32_e32 v34, 7, v67
	v_lshlrev_b32_e32 v32, 13, v34
	v_lshlrev_b32_e32 v33, 2, v35
	v_add3_u32 v32, 0, v32, v33
	s_waitcnt lgkmcnt(0)
	s_barrier
	ds_read2st64_b32 v[36:37], v32 offset1:2
	v_cmp_lt_i32_e32 vcc, 0, v34
	s_waitcnt lgkmcnt(0)
	v_add_f32_e32 v33, 0, v36
	v_add_f32_e32 v38, v33, v37
	ds_read2st64_b32 v[36:37], v32 offset0:4 offset1:6
	ds_write2st64_b32 v32, v33, v38 offset1:2
	s_waitcnt lgkmcnt(1)
	v_add_f32_e32 v33, v38, v36
	v_add_f32_e32 v38, v33, v37
	ds_read2st64_b32 v[36:37], v32 offset0:8 offset1:10
	ds_write2st64_b32 v32, v33, v38 offset0:4 offset1:6
	s_waitcnt lgkmcnt(1)
	v_add_f32_e32 v33, v38, v36
	v_add_f32_e32 v38, v33, v37
	ds_read2st64_b32 v[36:37], v32 offset0:12 offset1:14
	ds_write2st64_b32 v32, v33, v38 offset0:8 offset1:10
	s_waitcnt lgkmcnt(1)
	v_add_f32_e32 v33, v38, v36
	v_add_f32_e32 v38, v33, v37
	ds_read2st64_b32 v[36:37], v32 offset0:16 offset1:18
	ds_write2st64_b32 v32, v33, v38 offset0:12 offset1:14
	s_waitcnt lgkmcnt(1)
	v_add_f32_e32 v33, v38, v36
	v_add_f32_e32 v38, v33, v37
	ds_read2st64_b32 v[36:37], v32 offset0:20 offset1:22
	ds_write2st64_b32 v32, v33, v38 offset0:16 offset1:18
	s_waitcnt lgkmcnt(1)
	v_add_f32_e32 v33, v38, v36
	v_add_f32_e32 v38, v33, v37
	ds_read2st64_b32 v[36:37], v32 offset0:24 offset1:26
	ds_write2st64_b32 v32, v33, v38 offset0:20 offset1:22
	s_waitcnt lgkmcnt(1)
	v_add_f32_e32 v33, v38, v36
	v_add_f32_e32 v38, v33, v37
	ds_read2st64_b32 v[36:37], v32 offset0:28 offset1:30
	ds_write2st64_b32 v32, v33, v38 offset0:24 offset1:26
	s_waitcnt lgkmcnt(1)
	v_add_f32_e32 v33, v38, v36
	v_add_f32_e32 v36, v33, v37
	ds_write2st64_b32 v32, v33, v36 offset0:28 offset1:30
	v_mov_b32_e32 v33, 0
	s_waitcnt lgkmcnt(0)
	s_barrier
	s_and_saveexec_b64 s[2:3], vcc
	s_cbranch_execz .LBB0_828
	v_lshl_add_u32 v35, v35, 2, s60
	v_mov_b32_e32 v33, 0
	s_mov_b64 s[34:35], 0

; __device__ __forceinline__ u32x4 pack8(const f32x4& v0, const f32x4& v1) { u32x4 w; w.x = cvt_pk_bf16(v0[0], v0[1]); w.y = cvt_pk_bf16(v0[2], v0[3]); w.z = cvt_pk_bf16(v1[0], v1[1]); w.w = cvt_pk_bf16(v1[2], v1[3]); return w; }
; __device__ __forceinline__ void unpack8(const u32x4& w, f32x4& v0, f32x4& v1) { v0[0] = bflo(w.x); v0[1] = bfhi(w.x); v0[2] = bflo(w.y); v0[3] = bfhi(w.y); v1[0] = bflo(w.z); v1[1] = bfhi(w.z); v1[2] = bflo(w.w); v1[3] = bfhi(w.w); }
; __device__ __forceinline__ void hg_cum(const u32x4 (&ev)[2], int l, int h, const float* hlb, float* cumS, float* lbS, int tid) {
;     ...
;     __syncthreads();
; #pragma unroll
;     for (int tt = 0; tt < 16; ++tt) cumS[(seg * 16 + tt) * 128 + k] += off;
;     __syncthreads();
; __device__ __forceinline__ void hgC_item(const Bufs& B, int l, int it, unsigned char* shm, const float* hlb, const float* hn) {
;     ...
;     for (int q = 0; q < 2; ++q) {
;         const int idx = tid + 512 * q, t = idx >> 4, k8 = (idx & 15) * 8;
;         f32x4 q0, q1, e0, e1; unpack8(qv[q], q0, q1); unpack8(ev[q], e0, e1);
;         const u32x4 iw = iv[q];
;         const int tx = t ^ (((k8 >> 3) & 7) << 3);
;         const f32x4 c0 = *(const f32x4*)(cumS + t * 128 + k8), c1 = *(const f32x4*)(cumS + t * 128 + k8 + 4), m0v = *(const f32x4*)(cumS + 31 * 128 + k8), m1v = *(const f32x4*)(cumS + 31 * 128 + k8 + 4);
;         const f32x4 l0 = *(const f32x4*)(lbS + k8), l1 = *(const f32x4*)(lbS + k8 + 4);
;         f32x4 x0, x1, y0, y1, z0, z1;
; #pragma unroll
;         for (int j = 0; j < 4; ++j) {
;             x0[j] = q0[j] * __expf(c0[j]); x1[j] = q1[j] * __expf(c1[j]);
;             y0[j] = q0[j] * __expf(fminf(c0[j] - m0v[j], 80.f)); y1[j] = q1[j] * __expf(fminf(c1[j] - m1v[j], 80.f));
;             z0[j] = l0[j] * e0[j] * __expf(fminf(m0v[j] - c0[j], 80.f)); z1[j] = l1[j] * e1[j] * __expf(fminf(m1v[j] - c1[j], 80.f));
;         }
;         *(u32x4*)(qe + t * 136 + k8) = pack8(x0, x1); *(u32x4*)(qa + t * 136 + k8) = pack8(y0, y1); *(u32x4*)(kb + t * 136 + k8) = pack8(z0, z1);
.LBB0_828:
	s_or_b64 exec, exec, s[2:3]
	s_barrier
	ds_read2st64_b32 v[34:35], v32 offset1:2
	v_lshlrev_b32_e32 v38, 16, v28
	v_and_b32_e32 v39, 0xffff0000, v28
	v_lshlrev_b32_e32 v86, 16, v29
	v_and_b32_e32 v87, 0xffff0000, v29
	s_waitcnt lgkmcnt(0)
	v_add_f32_e32 v34, v33, v34
	v_add_f32_e32 v35, v33, v35
	ds_write2st64_b32 v32, v34, v35 offset1:2
	ds_read2st64_b32 v[34:35], v32 offset0:4 offset1:6
	v_lshlrev_b32_e32 v88, 16, v30
	v_and_b32_e32 v89, 0xffff0000, v30
	v_lshlrev_b32_e32 v90, 16, v31
	v_and_b32_e32 v91, 0xffff0000, v31
	s_waitcnt lgkmcnt(0)
	v_add_f32_e32 v34, v33, v34
	v_add_f32_e32 v35, v33, v35
	ds_write2st64_b32 v32, v34, v35 offset0:4 offset1:6
	ds_read2st64_b32 v[34:35], v32 offset0:8 offset1:10
	v_sub_u32_e32 v100, v48, v42
	v_cmp_gt_i32_e32 vcc, 16, v66
	s_waitcnt lgkmcnt(0)
	v_add_f32_e32 v34, v33, v34
	v_add_f32_e32 v35, v33, v35
	ds_write2st64_b32 v32, v34, v35 offset0:8 offset1:10
	ds_read2st64_b32 v[34:35], v32 offset0:12 offset1:14
	s_waitcnt lgkmcnt(0)
	v_add_f32_e32 v34, v33, v34
	v_add_f32_e32 v35, v33, v35
	ds_write2st64_b32 v32, v34, v35 offset0:12 offset1:14
	ds_read2st64_b32 v[34:35], v32 offset0:16 offset1:18
	s_waitcnt lgkmcnt(0)
	v_add_f32_e32 v34, v33, v34
	v_add_f32_e32 v35, v33, v35
	ds_write2st64_b32 v32, v34, v35 offset0:16 offset1:18
	ds_read2st64_b32 v[34:35], v32 offset0:20 offset1:22
	s_waitcnt lgkmcnt(0)
	v_add_f32_e32 v34, v33, v34
	v_add_f32_e32 v35, v33, v35
	ds_write2st64_b32 v32, v34, v35 offset0:20 offset1:22
	ds_read2st64_b32 v[34:35], v32 offset0:24 offset1:26
	s_waitcnt lgkmcnt(0)
	v_add_f32_e32 v34, v33, v34
	v_add_f32_e32 v35, v33, v35
	ds_write2st64_b32 v32, v34, v35 offset0:24 offset1:26
	ds_read2st64_b32 v[34:35], v32 offset0:28 offset1:30
	s_waitcnt lgkmcnt(0)
	v_add_f32_e32 v34, v33, v34
	v_add_f32_e32 v33, v33, v35
	ds_write2st64_b32 v32, v34, v33 offset0:28 offset1:30
	v_lshl_add_u32 v34, v43, 9, v48
	s_waitcnt lgkmcnt(0)
	s_barrier
	ds_read_b128 v[28:31], v34
	ds_read_b128 v[34:37], v34 offset:16
	ds_read_b128 v[70:73], v48 offset:15872
	ds_read_b128 v[74:77], v48 offset:15888
	ds_read_b128 v[78:81], v69
	ds_read_b128 v[82:85], v69 offset:16
	s_waitcnt lgkmcnt(4)
	v_mul_f32_e32 v93, 0x3fb8aa3b, v34
	v_exp_f32_e32 v94, v93
	s_waitcnt lgkmcnt(3)
	v_sub_f32_e32 v93, v28, v70
	v_min_f32_e32 v93, 0x42a00000, v93
	v_mul_f32_e32 v93, 0x3fb8aa3b, v93
	v_exp_f32_e32 v96, v93
	s_waitcnt lgkmcnt(2)
	v_sub_f32_e32 v93, v34, v74
	v_min_f32_e32 v93, 0x42a00000, v93
	v_mul_f32_e32 v92, 0x3fb8aa3b, v28
	v_mul_f32_e32 v93, 0x3fb8aa3b, v93
	v_sub_f32_e32 v28, v70, v28
	v_mul_f32_e32 v70, 0x3fb8aa3b, v29
	v_exp_f32_e32 v98, v93
	v_exp_f32_e32 v93, v70
	v_mul_f32_e32 v70, 0x3fb8aa3b, v35
	v_exp_f32_e32 v95, v70
	v_sub_f32_e32 v70, v29, v71
	v_sub_f32_e32 v29, v71, v29
	v_min_f32_e32 v28, 0x42a00000, v28
	v_min_f32_e32 v29, 0x42a00000, v29
	v_mul_f32_e32 v28, 0x3fb8aa3b, v28
	v_mul_f32_e32 v29, 0x3fb8aa3b, v29
	v_exp_f32_e32 v28, v28
	v_exp_f32_e32 v29, v29
	s_waitcnt lgkmcnt(1)
	v_pk_mul_f32 v[56:57], v[78:79], v[56:57]
	v_sub_f32_e32 v34, v74, v34
	v_min_f32_e32 v34, 0x42a00000, v34
	v_pk_mul_f32 v[56:57], v[56:57], v[28:29]
	v_sub_f32_e32 v28, v75, v35
	v_min_f32_e32 v70, 0x42a00000, v70
	v_min_f32_e32 v28, 0x42a00000, v28
	v_mul_f32_e32 v34, 0x3fb8aa3b, v34
	v_mul_f32_e32 v70, 0x3fb8aa3b, v70
	v_mul_f32_e32 v28, 0x3fb8aa3b, v28
	v_exp_f32_e32 v34, v34
	v_exp_f32_e32 v97, v70
	v_sub_f32_e32 v70, v35, v75
	v_exp_f32_e32 v35, v28
	s_waitcnt lgkmcnt(0)
	v_pk_mul_f32 v[28:29], v[82:83], v[54:55]
	v_min_f32_e32 v70, 0x42a00000, v70
	v_mul_f32_e32 v70, 0x3fb8aa3b, v70
	v_pk_mul_f32 v[34:35], v[28:29], v[34:35]
	v_mul_f32_e32 v29, 0x3fb8aa3b, v36
	v_exp_f32_e32 v54, v29
	v_sub_f32_e32 v29, v30, v72
	v_min_f32_e32 v29, 0x42a00000, v29
	v_mul_f32_e32 v29, 0x3fb8aa3b, v29
	v_exp_f32_e32 v99, v70
	v_exp_f32_e32 v70, v29
	v_sub_f32_e32 v29, v36, v76
	v_min_f32_e32 v29, 0x42a00000, v29
	v_mul_f32_e32 v29, 0x3fb8aa3b, v29
	v_exp_f32_e32 v74, v29
	v_sub_f32_e32 v29, v72, v30
	v_min_f32_e32 v29, 0x42a00000, v29
	v_mul_f32_e32 v29, 0x3fb8aa3b, v29
	v_mul_f32_e32 v28, 0x3fb8aa3b, v30
	v_exp_f32_e32 v30, v29
	v_sub_f32_e32 v29, v76, v36
	v_min_f32_e32 v29, 0x42a00000, v29
	v_mul_f32_e32 v29, 0x3fb8aa3b, v29
	v_exp_f32_e32 v36, v29
	v_mul_f32_e32 v29, 0x3fb8aa3b, v31
	v_exp_f32_e32 v28, v28
	v_exp_f32_e32 v29, v29
	v_sub_f32_e32 v71, v31, v73
	v_exp_f32_e32 v92, v92
	v_mul_f32_e32 v55, 0x3fb8aa3b, v37
	v_pk_mul_f32 v[78:79], v[28:29], v[86:87]
	v_sub_f32_e32 v28, v37, v77
	v_min_f32_e32 v28, 0x42a00000, v28
	v_mul_f32_e32 v28, 0x3fb8aa3b, v28
	v_exp_f32_e32 v75, v28
	v_sub_f32_e32 v28, v73, v31
	v_min_f32_e32 v28, 0x42a00000, v28
	v_mul_f32_e32 v28, 0x3fb8aa3b, v28
	v_exp_f32_e32 v31, v28
	v_pk_mul_f32 v[28:29], v[80:81], v[52:53]
	v_min_f32_e32 v71, 0x42a00000, v71
	v_exp_f32_e32 v55, v55
	v_pk_mul_f32 v[52:53], v[28:29], v[30:31]
	v_sub_f32_e32 v28, v77, v37
	v_min_f32_e32 v28, 0x42a00000, v28
	v_mul_f32_e32 v28, 0x3fb8aa3b, v28
	v_mul_f32_e32 v71, 0x3fb8aa3b, v71
	v_exp_f32_e32 v37, v28
	v_exp_f32_e32 v71, v71
	v_pk_mul_f32 v[96:97], v[96:97], v[38:39]
	v_pk_mul_f32 v[38:39], v[92:93], v[38:39]
	v_pk_mul_f32 v[28:29], v[84:85], v[50:51]
	v_pk_mul_f32 v[92:93], v[98:99], v[88:89]
	v_pk_mul_f32 v[88:89], v[94:95], v[88:89]
	v_pk_mul_f32 v[54:55], v[54:55], v[90:91]
	v_pk_mul_f32 v[36:37], v[28:29], v[36:37]
	v_cvt_pk_bf16_f32 v28, v38, v39
	v_mul_lo_u32 v38, v43, s77
	v_pk_mul_f32 v[70:71], v[70:71], v[86:87]
	v_pk_mul_f32 v[74:75], v[74:75], v[90:91]
	v_cvt_pk_bf16_f32 v29, v78, v79
	v_cvt_pk_bf16_f32 v30, v88, v89
	v_cvt_pk_bf16_f32 v31, v54, v55
	v_add_u32_e32 v39, v100, v38
	v_add_u32_e32 v32, s46, v42
	v_mov_b32_e32 v33, s84
	ds_write_b128 v39, v[28:31] offset:33792
	v_cvt_pk_bf16_f32 v28, v96, v97
	v_cvt_pk_bf16_f32 v29, v70, v71
	v_cvt_pk_bf16_f32 v30, v92, v93
	v_cvt_pk_bf16_f32 v31, v74, v75
	v_mad_u32_u24 v33, v65, s76, v33
	v_bitop3_b32 v50, v68, v43, 56 bitop3:0x6c
	ds_write_b128 v39, v[28:31] offset:51200
	v_cvt_pk_bf16_f32 v28, v56, v57
	v_cvt_pk_bf16_f32 v29, v52, v53
	v_cvt_pk_bf16_f32 v30, v34, v35
	v_cvt_pk_bf16_f32 v31, v36, v37
	v_add_u32_e32 v34, v32, v38
	ds_write_b128 v34, v[28:31]
	v_lshl_add_u32 v28, v50, 1, v33
	ds_write_b16 v28, v24
	ds_write_b16_d16_hi v28, v24 offset:144
	ds_write_b16 v28, v25 offset:288
	ds_write_b16_d16_hi v28, v25 offset:432
	ds_write_b16 v28, v26 offset:576
	ds_write_b16_d16_hi v28, v26 offset:720
	ds_write_b16 v28, v27 offset:864
	ds_write_b16_d16_hi v28, v27 offset:1008
	v_lshl_add_u32 v24, v49, 9, v48
	v_lshlrev_b32_e32 v38, 16, v20
	v_and_b32_e32 v39, 0xffff0000, v20
	v_lshlrev_b32_e32 v70, 16, v21
	v_and_b32_e32 v71, 0xffff0000, v21
	v_lshlrev_b32_e32 v72, 16, v22
	v_and_b32_e32 v73, 0xffff0000, v22
	v_lshlrev_b32_e32 v74, 16, v23
	v_and_b32_e32 v75, 0xffff0000, v23
	ds_read_b128 v[20:23], v24
	ds_read_b128 v[24:27], v24 offset:16
	ds_read_b128 v[28:31], v48 offset:15872
	ds_read_b128 v[34:37], v48 offset:15888
	ds_read_b128 v[50:53], v69
	ds_read_b128 v[54:57], v69 offset:16
	s_waitcnt lgkmcnt(5)
; __device__ __forceinline__ u32x4 pack8(const f32x4& v0, const f32x4& v1) { u32x4 w; w.x = cvt_pk_bf16(v0[0], v0[1]); w.y = cvt_pk_bf16(v0[2], v0[3]); w.z = cvt_pk_bf16(v1[0], v1[1]); w.w = cvt_pk_bf16(v1[2], v1[3]); return w; }
; __device__ __forceinline__ void unpack8(const u32x4& w, f32x4& v0, f32x4& v1) { v0[0] = bflo(w.x); v0[1] = bfhi(w.x); v0[2] = bflo(w.y); v0[3] = bfhi(w.y); v1[0] = bflo(w.z); v1[1] = bfhi(w.z); v1[2] = bflo(w.w); v1[3] = bfhi(w.w); }
; __device__ __forceinline__ void hgC_item(const Bufs& B, int l, int it, unsigned char* shm, const float* hlb, const float* hn) {
;     ...
;     for (int q = 0; q < 2; ++q) {
;         const int idx = tid + 512 * q, t = idx >> 4, k8 = (idx & 15) * 8;
;         f32x4 q0, q1, e0, e1; unpack8(qv[q], q0, q1); unpack8(ev[q], e0, e1);
;         const u32x4 iw = iv[q];
;         const int tx = t ^ (((k8 >> 3) & 7) << 3);
;         const f32x4 c0 = *(const f32x4*)(cumS + t * 128 + k8), c1 = *(const f32x4*)(cumS + t * 128 + k8 + 4), m0v = *(const f32x4*)(cumS + 31 * 128 + k8), m1v = *(const f32x4*)(cumS + 31 * 128 + k8 + 4);
;         const f32x4 l0 = *(const f32x4*)(lbS + k8), l1 = *(const f32x4*)(lbS + k8 + 4);
;         f32x4 x0, x1, y0, y1, z0, z1;
; #pragma unroll
;         for (int j = 0; j < 4; ++j) {
;             x0[j] = q0[j] * __expf(c0[j]); x1[j] = q1[j] * __expf(c1[j]);
;             y0[j] = q0[j] * __expf(fminf(c0[j] - m0v[j], 80.f)); y1[j] = q1[j] * __expf(fminf(c1[j] - m1v[j], 80.f));
;             z0[j] = l0[j] * e0[j] * __expf(fminf(m0v[j] - c0[j], 80.f)); z1[j] = l1[j] * e1[j] * __expf(fminf(m1v[j] - c1[j], 80.f));
;         }
;         *(u32x4*)(qe + t * 136 + k8) = pack8(x0, x1); *(u32x4*)(qa + t * 136 + k8) = pack8(y0, y1); *(u32x4*)(kb + t * 136 + k8) = pack8(z0, z1);
;         iT[(k8 + 0) * 72 + tx] = (bf16_t)(iw.x & 0xffffu); iT[(k8 + 1) * 72 + tx] = (bf16_t)(iw.x >> 16); iT[(k8 + 2) * 72 + tx] = (bf16_t)(iw.y & 0xffffu); iT[(k8 + 3) * 72 + tx] = (bf16_t)(iw.y >> 16);
;         iT[(k8 + 4) * 72 + tx] = (bf16_t)(iw.z & 0xffffu); iT[(k8 + 5) * 72 + tx] = (bf16_t)(iw.z >> 16); iT[(k8 + 6) * 72 + tx] = (bf16_t)(iw.w & 0xffffu); iT[(k8 + 7) * 72 + tx] = (bf16_t)(iw.w >> 16);
;     }
;     __syncthreads();
	v_mul_f32_e32 v69, 0x3fb8aa3b, v20
	v_exp_f32_e32 v76, v69
	s_waitcnt lgkmcnt(4)
	v_mul_f32_e32 v69, 0x3fb8aa3b, v24
	v_exp_f32_e32 v78, v69
	s_waitcnt lgkmcnt(3)
	v_sub_f32_e32 v69, v20, v28
	v_sub_f32_e32 v20, v28, v20
	v_mul_f32_e32 v28, 0x3fb8aa3b, v21
	v_exp_f32_e32 v77, v28
	v_mul_f32_e32 v28, 0x3fb8aa3b, v25
	v_exp_f32_e32 v79, v28
	v_sub_f32_e32 v28, v21, v29
	v_sub_f32_e32 v21, v29, v21
	v_min_f32_e32 v20, 0x42a00000, v20
	v_min_f32_e32 v28, 0x42a00000, v28
	v_min_f32_e32 v21, 0x42a00000, v21
	v_mul_f32_e32 v20, 0x3fb8aa3b, v20
	v_mul_f32_e32 v28, 0x3fb8aa3b, v28
	v_mul_f32_e32 v21, 0x3fb8aa3b, v21
	v_exp_f32_e32 v20, v20
	v_exp_f32_e32 v81, v28
	s_waitcnt lgkmcnt(2)
	v_sub_f32_e32 v28, v25, v35
	v_exp_f32_e32 v21, v21
	v_min_f32_e32 v28, 0x42a00000, v28
	v_min_f32_e32 v69, 0x42a00000, v69
	v_mul_f32_e32 v28, 0x3fb8aa3b, v28
	v_mul_f32_e32 v69, 0x3fb8aa3b, v69
	v_exp_f32_e32 v83, v28
	s_waitcnt lgkmcnt(1)
	v_pk_mul_f32 v[28:29], v[50:51], v[62:63]
	v_exp_f32_e32 v80, v69
	v_sub_f32_e32 v69, v24, v34
	v_sub_f32_e32 v24, v34, v24
	v_pk_mul_f32 v[28:29], v[28:29], v[20:21]
	v_sub_f32_e32 v20, v35, v25
	v_min_f32_e32 v24, 0x42a00000, v24
	v_min_f32_e32 v20, 0x42a00000, v20
	v_mul_f32_e32 v24, 0x3fb8aa3b, v24
	v_mul_f32_e32 v20, 0x3fb8aa3b, v20
	v_exp_f32_e32 v24, v24
	v_exp_f32_e32 v25, v20
	s_waitcnt lgkmcnt(0)
	v_pk_mul_f32 v[20:21], v[54:55], v[60:61]
	v_min_f32_e32 v69, 0x42a00000, v69
	v_mul_f32_e32 v69, 0x3fb8aa3b, v69
	v_pk_mul_f32 v[24:25], v[20:21], v[24:25]
	v_mul_f32_e32 v21, 0x3fb8aa3b, v26
	v_exp_f32_e32 v34, v21
	v_sub_f32_e32 v21, v22, v30
	v_min_f32_e32 v21, 0x42a00000, v21
	v_mul_f32_e32 v21, 0x3fb8aa3b, v21
	v_exp_f32_e32 v50, v21
	v_sub_f32_e32 v21, v26, v36
	v_min_f32_e32 v21, 0x42a00000, v21
	v_mul_f32_e32 v21, 0x3fb8aa3b, v21
	v_exp_f32_e32 v54, v21
	v_sub_f32_e32 v21, v30, v22
	v_min_f32_e32 v21, 0x42a00000, v21
	v_mul_f32_e32 v21, 0x3fb8aa3b, v21
	v_mul_f32_e32 v20, 0x3fb8aa3b, v22
	v_exp_f32_e32 v22, v21
	v_sub_f32_e32 v21, v36, v26
	v_min_f32_e32 v21, 0x42a00000, v21
	v_mul_f32_e32 v21, 0x3fb8aa3b, v21
	v_exp_f32_e32 v26, v21
	v_mul_f32_e32 v21, 0x3fb8aa3b, v23
	v_exp_f32_e32 v20, v20
	v_exp_f32_e32 v21, v21
	v_mul_f32_e32 v30, 0x3fb8aa3b, v27
	v_exp_f32_e32 v35, v30
	v_sub_f32_e32 v30, v23, v31
	v_pk_mul_f32 v[60:61], v[20:21], v[70:71]
	v_sub_f32_e32 v20, v27, v37
	v_min_f32_e32 v20, 0x42a00000, v20
	v_mul_f32_e32 v20, 0x3fb8aa3b, v20
	v_exp_f32_e32 v55, v20
	v_sub_f32_e32 v20, v31, v23
	v_min_f32_e32 v20, 0x42a00000, v20
	v_mul_f32_e32 v20, 0x3fb8aa3b, v20
	v_exp_f32_e32 v23, v20
	v_min_f32_e32 v30, 0x42a00000, v30
	v_mul_f32_e32 v30, 0x3fb8aa3b, v30
	v_pk_mul_f32 v[20:21], v[52:53], v[58:59]
	v_exp_f32_e32 v51, v30
	v_pk_mul_f32 v[30:31], v[20:21], v[22:23]
	v_sub_f32_e32 v20, v37, v27
	v_min_f32_e32 v20, 0x42a00000, v20
	v_exp_f32_e32 v82, v69
	v_mul_f32_e32 v20, 0x3fb8aa3b, v20
	v_exp_f32_e32 v27, v20
	v_pk_mul_f32 v[34:35], v[34:35], v[74:75]
	v_pk_mul_f32 v[80:81], v[80:81], v[38:39]
	v_pk_mul_f32 v[38:39], v[76:77], v[38:39]
	v_pk_mul_f32 v[76:77], v[82:83], v[72:73]
	v_pk_mul_f32 v[72:73], v[78:79], v[72:73]
	v_pk_mul_f32 v[20:21], v[56:57], v[40:41]
	v_cvt_pk_bf16_f32 v23, v34, v35
	v_mul_lo_u32 v34, v49, s77
	v_pk_mul_f32 v[50:51], v[50:51], v[70:71]
	v_pk_mul_f32 v[54:55], v[54:55], v[74:75]
	v_pk_mul_f32 v[26:27], v[20:21], v[26:27]
	v_cvt_pk_bf16_f32 v20, v38, v39
	v_cvt_pk_bf16_f32 v21, v60, v61
	v_cvt_pk_bf16_f32 v22, v72, v73
	v_add_u32_e32 v35, v100, v34
	ds_write_b128 v35, v[20:23] offset:33792
	v_cvt_pk_bf16_f32 v20, v80, v81
	v_cvt_pk_bf16_f32 v21, v50, v51
	v_cvt_pk_bf16_f32 v22, v76, v77
	v_cvt_pk_bf16_f32 v23, v54, v55
	v_bitop3_b32 v36, v49, v68, 56 bitop3:0x78
	ds_write_b128 v35, v[20:23] offset:51200
	v_cvt_pk_bf16_f32 v20, v28, v29
	v_cvt_pk_bf16_f32 v21, v30, v31
	v_cvt_pk_bf16_f32 v22, v24, v25
	v_cvt_pk_bf16_f32 v23, v26, v27
	v_add_u32_e32 v24, v32, v34
	ds_write_b128 v24, v[20:23]
	v_lshl_add_u32 v20, v36, 1, v33
	ds_write_b16 v20, v16
	ds_write_b16_d16_hi v20, v16 offset:144
	ds_write_b16 v20, v17 offset:288
	ds_write_b16_d16_hi v20, v17 offset:432
	ds_write_b16 v20, v18 offset:576
	ds_write_b16_d16_hi v20, v18 offset:720
	ds_write_b16 v20, v19 offset:864
	ds_write_b16_d16_hi v20, v19 offset:1008
	v_lshrrev_b32_e32 v16, 2, v67
	v_and_b32_e32 v21, 15, v67
	v_and_b32_e32 v23, 12, v16
	s_waitcnt lgkmcnt(0)
	s_barrier
; __device__ __forceinline__ bf16_t f2bf(float f) { unsigned u = __float_as_uint(f); u += 0x7FFFu + ((u >> 16) & 1u); return (bf16_t)(u >> 16); }
; __device__ __forceinline__ void hgC_item(const Bufs& B, int l, int it, unsigned char* shm, const float* hlb, const float* hn) {
;     ...
;     for (int tile = wid; tile < 16; tile += 8) {
;         const int tm = tile >> 2, tn = tile & 3;
;         f32x4 acc = {0.f, 0.f, 0.f, 0.f};
;         if (tn <= tm) acc = mma_tile(qa + tm * 16 * 136, 136, kb + tn * 16 * 136, 136, 128, lane);
;         const int sc = tn * 16 + (lane & 15);
; #pragma unroll
;         for (int j = 0; j < 4; ++j) { const int t = tm * 16 + (lane >> 4) * 4 + j; P[t * 72 + sc] = f2bf(sc <= t ? acc[j] : 0.f); }
;     }
	s_mov_b64 s[2:3], exec
	v_readfirstlane_b32 s34, v66
	v_mad_u32_u24 v20, v21, s77, v176
	v_and_b32_e32 v24, 3, v66
	v_mul_u32_u24_e32 v17, 0x1100, v24
	v_lshl_or_b32 v25, v24, 4, v21
	v_add3_u32 v26, s46, v20, v17
	v_lshl_add_u32 v22, v25, 1, s47
	s_lshr_b32 s34, s34, 2
	s_mul_i32 s35, s34, 0x1100
	s_lshl_b32 s34, s34, 4
	ds_read_b128 v[80:83], v26
	ds_read_b128 v[84:87], v26 offset:64
	ds_read_b128 v[88:91], v26 offset:128
	ds_read_b128 v[92:95], v26 offset:192
	v_add_u32_e32 v27, s35, v20
	ds_read_b128 v[96:99], v27 offset:51200
	ds_read_b128 v[100:103], v27 offset:51264
	ds_read_b128 v[104:107], v27 offset:51328
	ds_read_b128 v[108:111], v27 offset:51392
	ds_read_b128 v[112:115], v27 offset:59904
	ds_read_b128 v[116:119], v27 offset:59968
	ds_read_b128 v[120:123], v27 offset:60032
	ds_read_b128 v[124:127], v27 offset:60096
	v_add_u32_e32 v72, s34, v23
	v_mad_u32_u24 v75, v72, s76, v22
	s_waitcnt lgkmcnt(3)
	v_mfma_f32_16x16x32_bf16 v[60:63], v[96:99], v[80:83], 0
	v_mfma_f32_16x16x32_bf16 v[68:71], v[112:115], v[80:83], 0
	s_waitcnt lgkmcnt(2)
	v_mfma_f32_16x16x32_bf16 v[60:63], v[100:103], v[84:87], v[60:63]
	v_mfma_f32_16x16x32_bf16 v[68:71], v[116:119], v[84:87], v[68:71]
	s_waitcnt lgkmcnt(1)
	v_mfma_f32_16x16x32_bf16 v[60:63], v[104:107], v[88:91], v[60:63]
	v_mfma_f32_16x16x32_bf16 v[68:71], v[120:123], v[88:91], v[68:71]
	s_waitcnt lgkmcnt(0)
	v_mfma_f32_16x16x32_bf16 v[60:63], v[108:111], v[92:95], v[60:63]
	v_mfma_f32_16x16x32_bf16 v[68:71], v[124:127], v[92:95], v[68:71]
	s_nop 7
	s_nop 3
	v_add_u32_e32 v73, 1, v72
	v_add_u32_e32 v74, 2, v72
	v_add_u32_e32 v76, 3, v72
	v_cmp_le_i32_e64 s[36:37], v25, v72
	v_cmp_le_i32_e64 s[38:39], v25, v73
	v_cmp_le_i32_e64 s[40:41], v25, v74
	v_cmp_le_i32_e64 vcc, v25, v76
	v_cndmask_b32_e64 v60, 0, v60, s[36:37]
	v_cndmask_b32_e64 v61, 0, v61, s[38:39]
	v_cndmask_b32_e64 v62, 0, v62, s[40:41]
	v_cndmask_b32_e64 v63, 0, v63, vcc
	v_bfe_u32 v77, v60, 16, 1
	v_bfe_u32 v73, v61, 16, 1
	v_bfe_u32 v74, v62, 16, 1
	v_bfe_u32 v76, v63, 16, 1
	v_add3_u32 v60, v60, v77, s78
	ds_write_b16_d16_hi v75, v60
	v_add3_u32 v61, v61, v73, s78
	ds_write_b16_d16_hi v75, v61 offset:144
	v_add3_u32 v62, v62, v74, s78
	ds_write_b16_d16_hi v75, v62 offset:288
	v_add3_u32 v63, v63, v76, s78
	ds_write_b16_d16_hi v75, v63 offset:432
	v_add_u32_e32 v72, 32, v72
	v_add_u32_e32 v73, 1, v72
	v_add_u32_e32 v74, 2, v72
	v_add_u32_e32 v76, 3, v72
	v_cmp_le_i32_e64 s[36:37], v25, v72
	v_cmp_le_i32_e64 s[38:39], v25, v73
	v_cmp_le_i32_e64 s[40:41], v25, v74
	v_cmp_le_i32_e64 vcc, v25, v76
	v_cndmask_b32_e64 v68, 0, v68, s[36:37]
	v_cndmask_b32_e64 v69, 0, v69, s[38:39]
	v_cndmask_b32_e64 v70, 0, v70, s[40:41]
	v_cndmask_b32_e64 v71, 0, v71, vcc
	v_bfe_u32 v77, v68, 16, 1
	v_bfe_u32 v73, v69, 16, 1
	v_bfe_u32 v74, v70, 16, 1
	v_bfe_u32 v76, v71, 16, 1
	v_add3_u32 v68, v68, v77, s78
	ds_write_b16_d16_hi v75, v68 offset:4608
	v_add3_u32 v69, v69, v73, s78
	ds_write_b16_d16_hi v75, v69 offset:4752
	v_add3_u32 v70, v70, v74, s78
	ds_write_b16_d16_hi v75, v70 offset:4896
	v_add3_u32 v71, v71, v76, s78
	ds_write_b16_d16_hi v75, v71 offset:5040
